# first grid barrier: the 16 per-XCC census counter loads issued back to back instead of one round trip each
# baseline (speedup 1.0000x reference)
; __device__ __forceinline__ unsigned xb_ld(unsigned* p)              { return __hip_atomic_load(p, __ATOMIC_RELAXED, __HIP_MEMORY_SCOPE_AGENT); }
; __device__ __forceinline__ void xcd_barrier_complete(unsigned* bar, unsigned x, unsigned& nloc, unsigned& nx) {
;     const unsigned G = gridDim.x * gridDim.y * gridDim.z;
;     unsigned sum, cnt, mine, sp = 0u;
;     for (;;) {
;         sum = 0u; cnt = 0u; mine = 0u;
; #pragma unroll
;         for (unsigned j = 0; j < 16; ++j) { const unsigned c = xb_ld(&bar[XB_XCNT(j)]); sum += c; cnt += (c > 0u) ? 1u : 0u; mine = (j == x) ? c : mine; }
;         if (sum == G) break;
;         __builtin_amdgcn_s_sleep(1);
;         if ((++sp & 255u) == 0u) { if (xb_ld(&bar[XB_TMO])) break; if (sp > XB_SPIN_CAP) { atomicAdd(&bar[XB_TMO], 1u); break; } }
;     }
;     nloc = mine > 0u ? mine : 1u; nx = cnt > 0u ? cnt : 1u;
; }
.LBB0_85:
	v_readlane_b32 s6, v251, 17
	v_readlane_b32 s7, v251, 18
	v_readlane_b32 s8, v253, 22
	s_waitcnt lgkmcnt(0)
	s_nop 2
	global_load_dword v0, v173, s[6:7] sc1
	v_readlane_b32 s6, v251, 19
	v_readlane_b32 s7, v251, 20
	s_nop 4
	global_load_dword v1, v173, s[6:7] sc1
	v_readlane_b32 s6, v251, 21
	v_readlane_b32 s7, v251, 22
	s_nop 4
	global_load_dword v2, v173, s[6:7] sc1
	v_readlane_b32 s6, v251, 23
	v_readlane_b32 s7, v251, 24
	s_nop 4
	global_load_dword v4, v173, s[6:7] sc1
	v_readlane_b32 s6, v251, 25
	v_readlane_b32 s7, v251, 26
	s_nop 4
	global_load_dword v5, v173, s[6:7] sc1
	v_readlane_b32 s6, v251, 27
	v_readlane_b32 s7, v251, 28
	s_nop 4
	global_load_dword v6, v173, s[6:7] sc1
	v_readlane_b32 s6, v251, 29
	v_readlane_b32 s7, v251, 30
	s_nop 4
	global_load_dword v7, v173, s[6:7] sc1
	v_readlane_b32 s6, v251, 31
	v_readlane_b32 s7, v251, 32
	s_nop 4
	global_load_dword v8, v173, s[6:7] sc1
	v_readlane_b32 s6, v251, 33
	v_readlane_b32 s7, v251, 34
	s_nop 4
	global_load_dword v9, v173, s[6:7] sc1
	v_readlane_b32 s6, v251, 35
	v_readlane_b32 s7, v251, 36
	s_nop 4
	global_load_dword v10, v173, s[6:7] sc1
	v_readlane_b32 s6, v251, 37
	v_readlane_b32 s7, v251, 38
	s_nop 4
	global_load_dword v11, v173, s[6:7] sc1
	v_readlane_b32 s6, v251, 39
	v_readlane_b32 s7, v251, 40
	s_nop 4
	global_load_dword v12, v173, s[6:7] sc1
	v_readlane_b32 s6, v251, 41
	v_readlane_b32 s7, v251, 42
	s_nop 4
	global_load_dword v13, v173, s[6:7] sc1
	v_readlane_b32 s6, v251, 43
	v_readlane_b32 s7, v251, 44
	s_nop 4
	global_load_dword v14, v173, s[6:7] sc1
	v_readlane_b32 s6, v251, 45
	v_readlane_b32 s7, v251, 46
	s_nop 4
	global_load_dword v15, v173, s[6:7] sc1
	v_readlane_b32 s6, v251, 47
	v_readlane_b32 s7, v251, 48
	s_nop 4
	global_load_dword v16, v173, s[6:7] sc1
	s_mov_b64 s[6:7], -1
	s_waitcnt vmcnt(0)
	v_add_u32_e32 v17, v1, v0
	v_add_u32_e32 v17, v17, v2
	v_add_u32_e32 v17, v17, v4
	v_add_u32_e32 v17, v17, v5
	v_add_u32_e32 v17, v17, v6
	v_add_u32_e32 v17, v17, v7
	v_add_u32_e32 v17, v17, v8
	v_add_u32_e32 v17, v17, v9
	v_add_u32_e32 v17, v17, v10
	v_add_u32_e32 v17, v17, v11
	v_add_u32_e32 v17, v17, v12
	v_add_u32_e32 v17, v17, v13
	v_add_u32_e32 v17, v17, v14
	v_add_u32_e32 v17, v17, v15
	v_add_u32_e32 v17, v17, v16
	v_cmp_eq_u32_e32 vcc, s8, v17
	s_mov_b64 s[8:9], -1
	s_cbranch_vccnz .LBB0_84
	s_and_b32 s6, s10, 0xff
	s_cmp_eq_u32 s6, 0
	s_mov_b64 s[6:7], -1
	s_mov_b64 s[12:13], -1
	s_sleep 1
	s_cbranch_scc1 .LBB0_89
	s_and_b64 vcc, exec, s[12:13]
	s_cbranch_vccz .LBB0_84
